# convert_layer: hand-written batched cache conversion (wide loads) and weight-transpose tile loads issued together instead of one round trip each
# speedup vs baseline: 1.0742x; 1.0123x over previous
; DI unsigned short f2bf(float x) { unsigned u = __float_as_uint(x); u += 0x7fffu + ((u >> 16) & 1u); return (unsigned short)(u >> 16); }
; DI int otid() { int t = threadIdx.x; asm volatile("" : "+v"(t)); return t; }
;   const int tid = otid();
; #pragma unroll
;   for (int rr = 0; rr < 8; ++rr) {
;     const int kl = rr * 8 + (tid >> 6), nl = tid & 63, np = n0 + nl;
;     int n = np; bool ok = true;
;     if (winmap) { if (np >= 3840) n = np - 56; else if (np >= 3784) ok = false; }
;     tile[kl * 65 + nl] = ok ? src[(size_t)(k0 + kl) * ldsrc + n] : 0.f;
;   }
; DI void convert_layer(const Params& p, int l, char* smem) {
;     ...
;   for (int idx = gtid; idx < 8 * 1024 * 512; idx += gn) {
;     int b = idx >> 19, rem = idx & ((1 << 19) - 1);
;     (reinterpret_cast<bf16_t*>(p.ws + OFF_KAS))[(size_t)b * LS * 512 + rem] = f2bf(p.c_sb_k[(size_t)l * 8 * 1024 * 512 + idx]);
;   }
; #pragma unroll 4
;   for (int idx = gtid; idx < 8 * 512 * 1024; idx += gn) {
;     int b = idx >> 19, hd = (idx >> 10) & 511, t = idx & 1023;
;     (reinterpret_cast<bf16_t*>(p.ws + OFF_VATS))[((size_t)b * 512 + hd) * LS + t] = f2bf(p.c_sb_v[(((size_t)l * 8 + b) * 1024 + t) * 512 + hd]);
;   }
;   for (int idx = gtid; idx < 8 * 1024 * 64; idx += gn) {
;     int b = idx >> 16, rem = idx & 65535;
;     (reinterpret_cast<bf16_t*>(p.ws + OFF_KBS))[(size_t)b * LS * 64 + rem] = f2bf(p.c_dsa_k[(size_t)l * 8 * 65536 + idx]);
;     (reinterpret_cast<bf16_t*>(p.ws + OFF_KIS))[(size_t)b * LS * 64 + rem] = f2bf(p.c_idx_k[(size_t)l * 8 * 65536 + idx]);
;     int d = (idx >> 10) & 63, t = idx & 1023;
;     (reinterpret_cast<bf16_t*>(p.ws + OFF_VBTS))[((size_t)b * 64 + d) * LS + t] = f2bf(p.c_dsa_v[(((size_t)l * 8 + b) * 1024 + t) * 64 + d]);
;   }
.LBB0_30:
	s_andn2_b64 vcc, exec, s[0:1]
	s_cbranch_vccnz .LBB0_19
	v_mov_b32_e32 v2, v153
	s_and_b32 s23, s15, 0x3c0
	v_bfi_b32 v4, 63, v2, s12
	v_subrev_u32_e32 v5, 56, v4
	v_add_u32_e32 v6, 0xfffff138, v4
	v_cmp_lt_i32_e64 s[0:1], s19, v4
	v_ashrrev_i32_e32 v1, 6, v2
	v_cmp_lt_u32_e32 vcc, 55, v6
	v_mov_b32_e32 v8, 0
	v_cndmask_b32_e64 v4, v4, v5, s[0:1]
	v_mov_b32_e32 v5, 0
	v_mov_b32_e32 v112, 0
	v_mov_b32_e32 v113, 0
	v_mov_b32_e32 v114, 0
	v_mov_b32_e32 v115, 0
	v_mov_b32_e32 v116, 0
	v_mov_b32_e32 v117, 0
	v_mov_b32_e32 v118, 0
	v_mov_b32_e32 v119, 0
	v_readlane_b32 s38, v249, 28
	v_readlane_b32 s39, v249, 29
	s_and_saveexec_b64 s[0:1], vcc
	s_cbranch_execz .Ltw0_skip
	v_add_u32_e32 v9, s23, v1
	v_ashrrev_i32_e32 v5, 31, v4
	v_mov_b64_e32 v[6:7], s[38:39]
	v_mad_i64_i32 v[6:7], s[26:27], v9, s20, v[6:7]
	v_lshl_add_u64 v[6:7], v[4:5], 2, v[6:7]
	s_mov_b64 s[28:29], 0x2d900
	global_load_dword v112, v[6:7], off
	v_lshl_add_u64 v[6:7], v[6:7], 0, s[28:29]
	global_load_dword v113, v[6:7], off
	v_lshl_add_u64 v[6:7], v[6:7], 0, s[28:29]
	global_load_dword v114, v[6:7], off
	v_lshl_add_u64 v[6:7], v[6:7], 0, s[28:29]
	global_load_dword v115, v[6:7], off
	v_lshl_add_u64 v[6:7], v[6:7], 0, s[28:29]
	global_load_dword v116, v[6:7], off
	v_lshl_add_u64 v[6:7], v[6:7], 0, s[28:29]
	global_load_dword v117, v[6:7], off
	v_lshl_add_u64 v[6:7], v[6:7], 0, s[28:29]
	global_load_dword v118, v[6:7], off
	v_lshl_add_u64 v[6:7], v[6:7], 0, s[28:29]
	global_load_dword v119, v[6:7], off
.Ltw0_skip:
	s_or_b64 exec, exec, s[0:1]
	v_and_b32_e32 v2, 63, v2
	v_lshl_add_u32 v7, v2, 2, 0
	v_mul_lo_u32 v6, v1, s17
	v_add_u32_e32 v9, v7, v6
	v_add_u32_e32 v6, 8, v1
	v_add_u32_e32 v8, 16, v1
	v_add_u32_e32 v10, 24, v1
	v_add_u32_e32 v11, 32, v1
	v_add_u32_e32 v12, 40, v1
	v_add_u32_e32 v13, 48, v1
	v_add_u32_e32 v14, 56, v1
	s_waitcnt vmcnt(0)
	ds_write_b32 v9, v112
	ds_write_b32 v9, v113 offset:2080
	ds_write_b32 v9, v114 offset:4160
	ds_write_b32 v9, v115 offset:6240
	ds_write_b32 v9, v116 offset:8320
	ds_write_b32 v9, v117 offset:10400
	ds_write_b32 v9, v118 offset:12480
	v_mov_b32_e32 v15, v119
	s_branch .LBB0_18
.LBB0_47:
	v_readlane_b32 s20, v249, 6
	s_nop 3
	s_cmpk_eq_i32 s20, 0x100
	s_cbranch_scc0 .Lcc0_old
	v_readlane_b32 s20, v249, 8
	v_readlane_b32 s24, v249, 0
	v_readlane_b32 s25, v249, 1
	v_readlane_b32 s26, v249, 14
	v_readlane_b32 s27, v249, 15
	v_readlane_b32 s28, v249, 16
	v_readlane_b32 s29, v249, 17
	v_readlane_b32 s30, v249, 18
	v_readlane_b32 s31, v249, 19
	v_readlane_b32 s32, v249, 20
	v_readlane_b32 s33, v249, 21
	v_readlane_b32 s34, v249, 22
	v_readlane_b32 s35, v249, 23
	s_mov_b32 s22, 0
	s_nop 3
	v_add_u32_e32 v18, s20, v153
	v_mov_b32_e32 v16, 0
	s_lshl_b32 s36, s22, 24
	s_lshl_b32 s37, s22, 21
	s_add_u32 s26, s26, s36
	s_addc_u32 s27, s27, 0
	s_add_u32 s28, s28, s36
	s_addc_u32 s29, s29, 0
	s_add_u32 s30, s30, s37
	s_addc_u32 s31, s31, 0
	s_add_u32 s32, s32, s37
	s_addc_u32 s33, s33, 0
	s_add_u32 s34, s34, s37
	s_addc_u32 s35, s35, 0
	v_lshlrev_b32_e32 v1, 4, v18
	v_lshlrev_b32_e32 v2, 3, v18
	v_and_b32_e32 v9, 0x3ff, v18
	v_lshrrev_b32_e32 v10, 10, v18
	v_lshlrev_b32_e32 v4, 11, v9
	v_lshl_add_u32 v4, v10, 4, v4
	v_lshlrev_b32_e32 v5, 1, v9
	v_mov_b32_e32 v11, 0x2200
	v_mad_u32_u24 v5, v10, v11, v5
	v_lshrrev_b32_e32 v12, 14, v18
	v_and_b32_e32 v13, 0x3fff, v18
	v_lshlrev_b32_e32 v6, 3, v13
	v_mov_b32_e32 v14, 0x22000
	v_mad_u32_u24 v6, v12, v14, v6
	v_bfe_u32 v15, v18, 10, 4
	v_lshlrev_b32_e32 v7, 18, v12
	v_lshl_add_u32 v7, v9, 8, v7
	v_lshl_add_u32 v7, v15, 4, v7
	v_lshlrev_b32_e32 v8, 1, v9
	v_mad_u32_u24 v8, v15, v11, v8
	v_mad_u32_u24 v8, v12, v14, v8
	s_add_u32 s38, s26, 0x0
	s_addc_u32 s39, s27, 0
	global_load_dwordx4 v[112:115], v1, s[38:39]
	s_add_u32 s40, s26, 0x200000
	s_addc_u32 s41, s27, 0
	global_load_dwordx4 v[116:119], v1, s[40:41]
	s_add_u32 s38, s26, 0x400000
	s_addc_u32 s39, s27, 0
	global_load_dwordx4 v[120:123], v1, s[38:39]
	s_add_u32 s40, s26, 0x600000
	s_addc_u32 s41, s27, 0
	global_load_dwordx4 v[124:127], v1, s[40:41]
	s_add_u32 s38, s26, 0x800000
	s_addc_u32 s39, s27, 0
	global_load_dwordx4 v[128:131], v1, s[38:39]
	s_add_u32 s40, s26, 0xa00000
	s_addc_u32 s41, s27, 0
	global_load_dwordx4 v[132:135], v1, s[40:41]
	s_add_u32 s38, s26, 0xc00000
	s_addc_u32 s39, s27, 0
	global_load_dwordx4 v[136:139], v1, s[38:39]
	s_add_u32 s40, s26, 0xe00000
	s_addc_u32 s41, s27, 0
	global_load_dwordx4 v[140:143], v1, s[40:41]
	s_add_u32 s38, s28, 0x0
	s_addc_u32 s39, s29, 0
	global_load_dwordx4 v[24:27], v4, s[38:39]
	s_add_u32 s40, s28, 0x200000
	s_addc_u32 s41, s29, 0
	global_load_dwordx4 v[28:31], v4, s[40:41]
	s_add_u32 s38, s28, 0x400000
	s_addc_u32 s39, s29, 0
	global_load_dwordx4 v[32:35], v4, s[38:39]
	s_add_u32 s40, s28, 0x600000
	s_addc_u32 s41, s29, 0
	global_load_dwordx4 v[36:39], v4, s[40:41]
	s_add_u32 s38, s28, 0x800000
	s_addc_u32 s39, s29, 0
	global_load_dwordx4 v[40:43], v4, s[38:39]
	s_add_u32 s40, s28, 0xa00000
	s_addc_u32 s41, s29, 0
	global_load_dwordx4 v[44:47], v4, s[40:41]
	s_add_u32 s38, s28, 0xc00000
	s_addc_u32 s39, s29, 0
	global_load_dwordx4 v[48:51], v4, s[38:39]
	s_add_u32 s40, s28, 0xe00000
	s_addc_u32 s41, s29, 0
	global_load_dwordx4 v[52:55], v4, s[40:41]
	global_load_dwordx4 v[144:147], v1, s[30:31]
	global_load_dwordx4 v[148:151], v1, s[34:35]
	global_load_dwordx4 v[56:59], v7, s[32:33]
	s_add_u32 s42, s24, 0x24380000
	s_addc_u32 s43, s25, 0
	s_waitcnt vmcnt(18)
	v_cvt_pk_bf16_f32 v112, v112, v113
	v_cvt_pk_bf16_f32 v113, v114, v115
	global_store_dwordx2 v2, v[112:113], s[42:43]
	s_add_u32 s44, s24, 0x24490000
	s_addc_u32 s45, s25, 0
	s_waitcnt vmcnt(18)
; DI unsigned short f2bf(float x) { unsigned u = __float_as_uint(x); u += 0x7fffu + ((u >> 16) & 1u); return (unsigned short)(u >> 16); }
; DI void convert_layer(const Params& p, int l, char* smem) {
;     ...
;   for (int idx = gtid; idx < 8 * 1024 * 512; idx += gn) {
;     int b = idx >> 19, rem = idx & ((1 << 19) - 1);
;     (reinterpret_cast<bf16_t*>(p.ws + OFF_KAS))[(size_t)b * LS * 512 + rem] = f2bf(p.c_sb_k[(size_t)l * 8 * 1024 * 512 + idx]);
;   }
; #pragma unroll 4
;   for (int idx = gtid; idx < 8 * 512 * 1024; idx += gn) {
;     int b = idx >> 19, hd = (idx >> 10) & 511, t = idx & 1023;
;     (reinterpret_cast<bf16_t*>(p.ws + OFF_VATS))[((size_t)b * 512 + hd) * LS + t] = f2bf(p.c_sb_v[(((size_t)l * 8 + b) * 1024 + t) * 512 + hd]);
;   }
;   for (int idx = gtid; idx < 8 * 1024 * 64; idx += gn) {
;     int b = idx >> 16, rem = idx & 65535;
;     (reinterpret_cast<bf16_t*>(p.ws + OFF_KBS))[(size_t)b * LS * 64 + rem] = f2bf(p.c_dsa_k[(size_t)l * 8 * 65536 + idx]);
;     (reinterpret_cast<bf16_t*>(p.ws + OFF_KIS))[(size_t)b * LS * 64 + rem] = f2bf(p.c_idx_k[(size_t)l * 8 * 65536 + idx]);
;     int d = (idx >> 10) & 63, t = idx & 1023;
;     (reinterpret_cast<bf16_t*>(p.ws + OFF_VBTS))[((size_t)b * 64 + d) * LS + t] = f2bf(p.c_dsa_v[(((size_t)l * 8 + b) * 1024 + t) * 64 + d]);
;   }
	v_cvt_pk_bf16_f32 v116, v116, v117
	v_cvt_pk_bf16_f32 v117, v118, v119
	global_store_dwordx2 v2, v[116:117], s[44:45]
	s_add_u32 s42, s24, 0x245a0000
	s_addc_u32 s43, s25, 0
	s_waitcnt vmcnt(18)
	v_cvt_pk_bf16_f32 v120, v120, v121
	v_cvt_pk_bf16_f32 v121, v122, v123
	global_store_dwordx2 v2, v[120:121], s[42:43]
	s_add_u32 s44, s24, 0x246b0000
	s_addc_u32 s45, s25, 0
	s_waitcnt vmcnt(18)
	v_cvt_pk_bf16_f32 v124, v124, v125
	v_cvt_pk_bf16_f32 v125, v126, v127
	global_store_dwordx2 v2, v[124:125], s[44:45]
	s_add_u32 s42, s24, 0x247c0000
	s_addc_u32 s43, s25, 0
	s_waitcnt vmcnt(18)
	v_cvt_pk_bf16_f32 v128, v128, v129
	v_cvt_pk_bf16_f32 v129, v130, v131
	global_store_dwordx2 v2, v[128:129], s[42:43]
	s_add_u32 s44, s24, 0x248d0000
	s_addc_u32 s45, s25, 0
	s_waitcnt vmcnt(18)
	v_cvt_pk_bf16_f32 v132, v132, v133
	v_cvt_pk_bf16_f32 v133, v134, v135
	global_store_dwordx2 v2, v[132:133], s[44:45]
	s_add_u32 s42, s24, 0x249e0000
	s_addc_u32 s43, s25, 0
	s_waitcnt vmcnt(18)
	v_cvt_pk_bf16_f32 v136, v136, v137
	v_cvt_pk_bf16_f32 v137, v138, v139
	global_store_dwordx2 v2, v[136:137], s[42:43]
	s_add_u32 s44, s24, 0x24af0000
	s_addc_u32 s45, s25, 0
	s_waitcnt vmcnt(18)
	v_cvt_pk_bf16_f32 v140, v140, v141
	v_cvt_pk_bf16_f32 v141, v142, v143
	global_store_dwordx2 v2, v[140:141], s[44:45]
	s_waitcnt vmcnt(18)
	s_add_u32 s42, s24, 0x24c00000
	s_addc_u32 s43, s25, 0
	v_cvt_pk_bf16_f32 v24, v16, v24
	global_store_short_d16_hi v5, v24, s[42:43]
	v_cvt_pk_bf16_f32 v25, v16, v25
	global_store_short_d16_hi v5, v25, s[42:43] offset:2176
	s_add_u32 s44, s24, 0x24c01100
	s_addc_u32 s45, s25, 0
	v_cvt_pk_bf16_f32 v26, v16, v26
	global_store_short_d16_hi v5, v26, s[44:45]
	v_cvt_pk_bf16_f32 v27, v16, v27
	global_store_short_d16_hi v5, v27, s[44:45] offset:2176
	s_waitcnt vmcnt(21)
	s_add_u32 s42, s24, 0x24d10000
	s_addc_u32 s43, s25, 0
	v_cvt_pk_bf16_f32 v28, v16, v28
	global_store_short_d16_hi v5, v28, s[42:43]
	v_cvt_pk_bf16_f32 v29, v16, v29
	global_store_short_d16_hi v5, v29, s[42:43] offset:2176
	s_add_u32 s44, s24, 0x24d11100
	s_addc_u32 s45, s25, 0
	v_cvt_pk_bf16_f32 v30, v16, v30
	global_store_short_d16_hi v5, v30, s[44:45]
	v_cvt_pk_bf16_f32 v31, v16, v31
	global_store_short_d16_hi v5, v31, s[44:45] offset:2176
	s_waitcnt vmcnt(24)
	s_add_u32 s42, s24, 0x24e20000
	s_addc_u32 s43, s25, 0
	v_cvt_pk_bf16_f32 v32, v16, v32
	global_store_short_d16_hi v5, v32, s[42:43]
	v_cvt_pk_bf16_f32 v33, v16, v33
	global_store_short_d16_hi v5, v33, s[42:43] offset:2176
	s_add_u32 s44, s24, 0x24e21100
	s_addc_u32 s45, s25, 0
	v_cvt_pk_bf16_f32 v34, v16, v34
	global_store_short_d16_hi v5, v34, s[44:45]
	v_cvt_pk_bf16_f32 v35, v16, v35
	global_store_short_d16_hi v5, v35, s[44:45] offset:2176
	s_waitcnt vmcnt(27)
	s_add_u32 s42, s24, 0x24f30000
	s_addc_u32 s43, s25, 0
	v_cvt_pk_bf16_f32 v36, v16, v36
	global_store_short_d16_hi v5, v36, s[42:43]
	v_cvt_pk_bf16_f32 v37, v16, v37
	global_store_short_d16_hi v5, v37, s[42:43] offset:2176
	s_add_u32 s44, s24, 0x24f31100
	s_addc_u32 s45, s25, 0
	v_cvt_pk_bf16_f32 v38, v16, v38
	global_store_short_d16_hi v5, v38, s[44:45]
	v_cvt_pk_bf16_f32 v39, v16, v39
	global_store_short_d16_hi v5, v39, s[44:45] offset:2176
	s_waitcnt vmcnt(30)
	s_add_u32 s42, s24, 0x25040000
	s_addc_u32 s43, s25, 0
	v_cvt_pk_bf16_f32 v40, v16, v40
	global_store_short_d16_hi v5, v40, s[42:43]
	v_cvt_pk_bf16_f32 v41, v16, v41
	global_store_short_d16_hi v5, v41, s[42:43] offset:2176
	s_add_u32 s44, s24, 0x25041100
	s_addc_u32 s45, s25, 0
	v_cvt_pk_bf16_f32 v42, v16, v42
	global_store_short_d16_hi v5, v42, s[44:45]
	v_cvt_pk_bf16_f32 v43, v16, v43
	global_store_short_d16_hi v5, v43, s[44:45] offset:2176
	s_waitcnt vmcnt(33)
	s_add_u32 s42, s24, 0x25150000
	s_addc_u32 s43, s25, 0
	v_cvt_pk_bf16_f32 v44, v16, v44
	global_store_short_d16_hi v5, v44, s[42:43]
	v_cvt_pk_bf16_f32 v45, v16, v45
	global_store_short_d16_hi v5, v45, s[42:43] offset:2176
	s_add_u32 s44, s24, 0x25151100
	s_addc_u32 s45, s25, 0
	v_cvt_pk_bf16_f32 v46, v16, v46
	global_store_short_d16_hi v5, v46, s[44:45]
	v_cvt_pk_bf16_f32 v47, v16, v47
	global_store_short_d16_hi v5, v47, s[44:45] offset:2176
	s_waitcnt vmcnt(36)
	s_add_u32 s42, s24, 0x25260000
	s_addc_u32 s43, s25, 0
	v_cvt_pk_bf16_f32 v48, v16, v48
	global_store_short_d16_hi v5, v48, s[42:43]
	v_cvt_pk_bf16_f32 v49, v16, v49
	global_store_short_d16_hi v5, v49, s[42:43] offset:2176
	s_add_u32 s44, s24, 0x25261100
	s_addc_u32 s45, s25, 0
	v_cvt_pk_bf16_f32 v50, v16, v50
	global_store_short_d16_hi v5, v50, s[44:45]
	v_cvt_pk_bf16_f32 v51, v16, v51
	global_store_short_d16_hi v5, v51, s[44:45] offset:2176
	s_waitcnt vmcnt(39)
	s_add_u32 s42, s24, 0x25370000
	s_addc_u32 s43, s25, 0
	v_cvt_pk_bf16_f32 v52, v16, v52
	global_store_short_d16_hi v5, v52, s[42:43]
	v_cvt_pk_bf16_f32 v53, v16, v53
	global_store_short_d16_hi v5, v53, s[42:43] offset:2176
	s_add_u32 s44, s24, 0x25371100
	s_addc_u32 s45, s25, 0
	v_cvt_pk_bf16_f32 v54, v16, v54
	global_store_short_d16_hi v5, v54, s[44:45]
	v_cvt_pk_bf16_f32 v55, v16, v55
	global_store_short_d16_hi v5, v55, s[44:45] offset:2176
	s_add_u32 s42, s24, 0x26c80000
	s_addc_u32 s43, s25, 0
	s_waitcnt vmcnt(42)
	v_cvt_pk_bf16_f32 v144, v144, v145
	v_cvt_pk_bf16_f32 v145, v146, v147
	global_store_dwordx2 v6, v[144:145], s[42:43]
	s_add_u32 s44, s24, 0x26ea0000
	s_addc_u32 s45, s25, 0
	s_waitcnt vmcnt(42)
	v_cvt_pk_bf16_f32 v148, v148, v149
	v_cvt_pk_bf16_f32 v149, v150, v151
	global_store_dwordx2 v6, v[148:149], s[44:45]
	s_waitcnt vmcnt(42)
	s_add_u32 s42, s24, 0x26d90000
	s_addc_u32 s43, s25, 0
	v_cvt_pk_bf16_f32 v56, v16, v56
	global_store_short_d16_hi v8, v56, s[42:43]
	v_cvt_pk_bf16_f32 v57, v16, v57
	global_store_short_d16_hi v8, v57, s[42:43] offset:2176
	s_add_u32 s44, s24, 0x26d91100
	s_addc_u32 s45, s25, 0
	v_cvt_pk_bf16_f32 v58, v16, v58
	global_store_short_d16_hi v8, v58, s[44:45]
	v_cvt_pk_bf16_f32 v59, v16, v59
	global_store_short_d16_hi v8, v59, s[44:45] offset:2176
	s_mov_b64 s[0:1], exec
	s_branch .LBB0_89

; DI unsigned short f2bf(float x) { unsigned u = __float_as_uint(x); u += 0x7fffu + ((u >> 16) & 1u); return (unsigned short)(u >> 16); }
; DI int otid() { int t = threadIdx.x; asm volatile("" : "+v"(t)); return t; }
;   const int tid = otid();
; #pragma unroll
;   for (int rr = 0; rr < 8; ++rr) {
;     const int kl = rr * 8 + (tid >> 6), nl = tid & 63, np = n0 + nl;
;     int n = np; bool ok = true;
;     if (winmap) { if (np >= 3840) n = np - 56; else if (np >= 3784) ok = false; }
;     tile[kl * 65 + nl] = ok ? src[(size_t)(k0 + kl) * ldsrc + n] : 0.f;
;   }
;   __syncthreads();
; #pragma unroll
;   for (int rr = 0; rr < 8; ++rr) {
;     const int nl = rr * 8 + (tid >> 6), kl = tid & 63;
;     dst[(size_t)(n0 + nl) * K + dk + k0 + kl] = f2bf(tile[kl * 65 + nl]);
;   }
;   __syncthreads();
; }
; DI void convert_layer(const Params& p, int l, char* smem) {
;     ...
;     else { int i = it - 1728; int nt = i >> 4, kt = i & 15; tconv_tile(p.w_out + (size_t)l * 1024 * 1024, 1024, 1024, (reinterpret_cast<bf16_t*>(p.ws + OFF_WOUTT)), nt * 64, kt * 64, false, tile); }
.LBB0_2777:
	s_cmpk_gt_i32 s20, 0x5bf
	s_mov_b64 s[0:1], -1
	s_cbranch_scc0 .LBB0_2787
	s_cmpk_gt_u32 s20, 0x63f
	s_cbranch_scc0 .LBB0_2784
	s_cmpk_gt_u32 s20, 0x6bf
	s_cbranch_scc0 .LBB0_2781
	v_mov_b32_e32 v0, v153
	s_and_b32 s1, s15, 0x3c0
	s_and_b32 s0, s17, 0x7fffffc0
	v_ashrrev_i32_e32 v4, 6, v0
	v_and_b32_e32 v5, 63, v0
	v_add_u32_e32 v0, s1, v4
	s_addk_i32 s0, 0xe500
	v_ashrrev_i32_e32 v1, 31, v0
	v_or_b32_e32 v16, s0, v5
	v_lshlrev_b64 v[0:1], 12, v[0:1]
	v_lshl_add_u64 v[0:1], s[4:5], 0, v[0:1]
	v_lshlrev_b64 v[2:3], 2, v[16:17]
	v_lshl_add_u64 v[0:1], v[0:1], 0, v[2:3]
	global_load_dword v112, v[0:1], off
	s_movk_i32 s21, 0x104
	v_lshlrev_b32_e32 v6, 2, v5
	v_mul_lo_u32 v1, v4, s21
	v_add3_u32 v6, 0, v6, v1
	v_add_u32_e32 v7, 8, v4
	v_add_u32_e32 v8, 16, v4
	v_add_u32_e32 v9, 24, v4
	v_add_u32_e32 v10, 32, v4
	v_add_u32_e32 v11, 40, v4
	v_add_u32_e32 v12, 48, v4
	v_add_u32_e32 v13, 56, v4
	v_readlane_b32 s21, v250, 46
	v_lshlrev_b32_e32 v16, 1, v5
	v_add_u32_e32 v0, s1, v7
	v_ashrrev_i32_e32 v1, 31, v0
	v_lshlrev_b64 v[0:1], 12, v[0:1]
	v_lshl_add_u64 v[0:1], s[4:5], 0, v[0:1]
	v_lshl_add_u64 v[0:1], v[0:1], 0, v[2:3]
	global_load_dword v113, v[0:1], off
	v_add_u32_e32 v0, s1, v8
	v_ashrrev_i32_e32 v1, 31, v0
	v_lshlrev_b64 v[0:1], 12, v[0:1]
	v_lshl_add_u64 v[0:1], s[4:5], 0, v[0:1]
	v_lshl_add_u64 v[0:1], v[0:1], 0, v[2:3]
	global_load_dword v114, v[0:1], off
	v_add_u32_e32 v0, s1, v9
	v_ashrrev_i32_e32 v1, 31, v0
	v_lshlrev_b64 v[0:1], 12, v[0:1]
	v_lshl_add_u64 v[0:1], s[4:5], 0, v[0:1]
	v_lshl_add_u64 v[0:1], v[0:1], 0, v[2:3]
	global_load_dword v115, v[0:1], off
	v_add_u32_e32 v0, s1, v10
	v_ashrrev_i32_e32 v1, 31, v0
	v_lshlrev_b64 v[0:1], 12, v[0:1]
	v_lshl_add_u64 v[0:1], s[4:5], 0, v[0:1]
	v_lshl_add_u64 v[0:1], v[0:1], 0, v[2:3]
	global_load_dword v116, v[0:1], off
	v_add_u32_e32 v0, s1, v11
	v_ashrrev_i32_e32 v1, 31, v0
	v_lshlrev_b64 v[0:1], 12, v[0:1]
	v_lshl_add_u64 v[0:1], s[4:5], 0, v[0:1]
	v_lshl_add_u64 v[0:1], v[0:1], 0, v[2:3]
	global_load_dword v117, v[0:1], off
	v_add_u32_e32 v0, s1, v12
	v_ashrrev_i32_e32 v1, 31, v0
	v_lshlrev_b64 v[0:1], 12, v[0:1]
	v_lshl_add_u64 v[0:1], s[4:5], 0, v[0:1]
	v_lshl_add_u64 v[0:1], v[0:1], 0, v[2:3]
	global_load_dword v118, v[0:1], off
	v_add_u32_e32 v0, s1, v13
	v_ashrrev_i32_e32 v1, 31, v0
	v_lshlrev_b64 v[0:1], 12, v[0:1]
	v_lshl_add_u64 v[0:1], s[4:5], 0, v[0:1]
	v_lshl_add_u64 v[0:1], v[0:1], 0, v[2:3]
	global_load_dword v119, v[0:1], off
	v_mul_u32_u24_e32 v2, 0x104, v5
	v_lshlrev_b32_e32 v3, 2, v4
	s_lshl_b32 s1, s1, 1
	s_add_u32 s22, s21, s1
	v_readlane_b32 s1, v250, 47
	s_addc_u32 s23, s1, 0
	s_movk_i32 s1, 0x7fff
	v_add_u32_e32 v4, s0, v4
	s_waitcnt vmcnt(0)
	ds_write_b32 v6, v112
	ds_write_b32 v6, v113 offset:2080
	ds_write_b32 v6, v114 offset:4160
	ds_write_b32 v6, v115 offset:6240
	ds_write_b32 v6, v116 offset:8320
	ds_write_b32 v6, v117 offset:10400
	ds_write_b32 v6, v118 offset:12480
	ds_write_b32 v6, v119 offset:14560
	v_add3_u32 v6, 0, v2, v3
	s_waitcnt lgkmcnt(0)
	s_barrier
	ds_read2_b32 v[2:3], v6 offset1:8
	v_lshl_add_u64 v[0:1], s[22:23], 0, v[16:17]
	s_waitcnt lgkmcnt(0)
	v_bfe_u32 v5, v2, 16, 1
	v_add3_u32 v2, v2, v5, s1
	v_ashrrev_i32_e32 v5, 31, v4
	v_lshlrev_b64 v[4:5], 11, v[4:5]
	v_lshl_add_u64 v[4:5], v[0:1], 0, v[4:5]
	global_store_short_d16_hi v[4:5], v2, off
	v_bfe_u32 v2, v3, 16, 1
	v_add3_u32 v4, v3, v2, s1
	v_add_u32_e32 v2, s0, v7
	v_ashrrev_i32_e32 v3, 31, v2
	v_lshlrev_b64 v[2:3], 11, v[2:3]
	v_lshl_add_u64 v[2:3], v[0:1], 0, v[2:3]
	global_store_short_d16_hi v[2:3], v4, off
	ds_read2_b32 v[2:3], v6 offset0:16 offset1:24
	s_waitcnt lgkmcnt(0)
	v_bfe_u32 v4, v2, 16, 1
	v_add3_u32 v2, v2, v4, s1
	v_add_u32_e32 v4, s0, v8
	v_ashrrev_i32_e32 v5, 31, v4
	v_lshlrev_b64 v[4:5], 11, v[4:5]
	v_lshl_add_u64 v[4:5], v[0:1], 0, v[4:5]
	global_store_short_d16_hi v[4:5], v2, off
	v_bfe_u32 v2, v3, 16, 1
	v_add3_u32 v4, v3, v2, s1
	v_add_u32_e32 v2, s0, v9
	v_ashrrev_i32_e32 v3, 31, v2
	v_lshlrev_b64 v[2:3], 11, v[2:3]
	v_lshl_add_u64 v[2:3], v[0:1], 0, v[2:3]
	global_store_short_d16_hi v[2:3], v4, off
	ds_read2_b32 v[2:3], v6 offset0:32 offset1:40
	s_waitcnt lgkmcnt(0)
	v_bfe_u32 v4, v2, 16, 1
	v_add3_u32 v2, v2, v4, s1
	v_add_u32_e32 v4, s0, v10
	v_ashrrev_i32_e32 v5, 31, v4
	v_lshlrev_b64 v[4:5], 11, v[4:5]
	v_lshl_add_u64 v[4:5], v[0:1], 0, v[4:5]
	global_store_short_d16_hi v[4:5], v2, off
	v_bfe_u32 v2, v3, 16, 1
	v_add3_u32 v4, v3, v2, s1
	v_add_u32_e32 v2, s0, v11
	v_ashrrev_i32_e32 v3, 31, v2
	v_lshlrev_b64 v[2:3], 11, v[2:3]
	v_lshl_add_u64 v[2:3], v[0:1], 0, v[2:3]
	global_store_short_d16_hi v[2:3], v4, off
	ds_read2_b32 v[2:3], v6 offset0:48 offset1:56
	s_waitcnt lgkmcnt(0)
	v_bfe_u32 v4, v2, 16, 1
	v_add3_u32 v2, v2, v4, s1
	v_add_u32_e32 v4, s0, v12
	v_ashrrev_i32_e32 v5, 31, v4
	v_lshlrev_b64 v[4:5], 11, v[4:5]
	v_lshl_add_u64 v[4:5], v[0:1], 0, v[4:5]
	global_store_short_d16_hi v[4:5], v2, off
	v_bfe_u32 v2, v3, 16, 1
	v_add3_u32 v4, v3, v2, s1
	v_add_u32_e32 v2, s0, v13
	v_ashrrev_i32_e32 v3, 31, v2
	v_lshlrev_b64 v[2:3], 11, v[2:3]
	v_lshl_add_u64 v[0:1], v[0:1], 0, v[2:3]
	global_store_short_d16_hi v[0:1], v4, off
	s_barrier
	s_mov_b64 s[0:1], 0
; DI unsigned short f2bf(float x) { unsigned u = __float_as_uint(x); u += 0x7fffu + ((u >> 16) & 1u); return (unsigned short)(u >> 16); }
; DI int otid() { int t = threadIdx.x; asm volatile("" : "+v"(t)); return t; }
;   const int tid = otid();
; #pragma unroll
;   for (int rr = 0; rr < 8; ++rr) {
;     const int kl = rr * 8 + (tid >> 6), nl = tid & 63, np = n0 + nl;
;     int n = np; bool ok = true;
;     if (winmap) { if (np >= 3840) n = np - 56; else if (np >= 3784) ok = false; }
;     tile[kl * 65 + nl] = ok ? src[(size_t)(k0 + kl) * ldsrc + n] : 0.f;
;   }
;   __syncthreads();
; #pragma unroll
;   for (int rr = 0; rr < 8; ++rr) {
;     const int nl = rr * 8 + (tid >> 6), kl = tid & 63;
;     dst[(size_t)(n0 + nl) * K + dk + k0 + kl] = f2bf(tile[kl * 65 + nl]);
;   }
;   __syncthreads();
; }
; DI void convert_layer(const Params& p, int l, char* smem) {
;     ...
;     else if (it < 1728) { int i = it - 1600; int nt = i >> 3, kt = i & 7; tconv_tile(p.w_pb + (size_t)l * 512 * 1024, 1024, 1024, (reinterpret_cast<bf16_t*>(p.ws + OFF_WPAT)), nt * 64, kt * 64, false, tile, 512); }
.LBB0_2781:
	s_andn2_b64 vcc, exec, s[0:1]
	s_cbranch_vccnz .LBB0_2783
	v_mov_b32_e32 v0, v153
	s_and_b32 s1, s15, 0x1c0
	s_and_b32 s0, s16, 0x3fc0
	v_ashrrev_i32_e32 v4, 6, v0
	v_and_b32_e32 v5, 63, v0
	v_add_u32_e32 v0, s1, v4
	s_addk_i32 s0, 0xce00
	v_ashrrev_i32_e32 v1, 31, v0
	v_or_b32_e32 v16, s0, v5
	v_lshlrev_b64 v[0:1], 12, v[0:1]
	v_lshl_add_u64 v[0:1], s[6:7], 0, v[0:1]
	v_lshlrev_b64 v[2:3], 2, v[16:17]
	v_lshl_add_u64 v[0:1], v[0:1], 0, v[2:3]
	global_load_dword v112, v[0:1], off
	s_movk_i32 s21, 0x104
	v_lshlrev_b32_e32 v6, 2, v5
	v_mul_lo_u32 v1, v4, s21
	v_add3_u32 v6, 0, v6, v1
	v_add_u32_e32 v7, 8, v4
	v_add_u32_e32 v8, 16, v4
	v_add_u32_e32 v9, 24, v4
	v_add_u32_e32 v10, 32, v4
	v_add_u32_e32 v11, 40, v4
	v_add_u32_e32 v12, 48, v4
	v_add_u32_e32 v13, 56, v4
	v_readlane_b32 s21, v250, 48
	v_lshlrev_b32_e32 v16, 1, v5
	v_add_u32_e32 v0, s1, v7
	v_ashrrev_i32_e32 v1, 31, v0
	v_lshlrev_b64 v[0:1], 12, v[0:1]
	v_lshl_add_u64 v[0:1], s[6:7], 0, v[0:1]
	v_lshl_add_u64 v[0:1], v[0:1], 0, v[2:3]
	global_load_dword v113, v[0:1], off
	v_add_u32_e32 v0, s1, v8
	v_ashrrev_i32_e32 v1, 31, v0
	v_lshlrev_b64 v[0:1], 12, v[0:1]
	v_lshl_add_u64 v[0:1], s[6:7], 0, v[0:1]
	v_lshl_add_u64 v[0:1], v[0:1], 0, v[2:3]
	global_load_dword v114, v[0:1], off
	v_add_u32_e32 v0, s1, v9
	v_ashrrev_i32_e32 v1, 31, v0
	v_lshlrev_b64 v[0:1], 12, v[0:1]
	v_lshl_add_u64 v[0:1], s[6:7], 0, v[0:1]
	v_lshl_add_u64 v[0:1], v[0:1], 0, v[2:3]
	global_load_dword v115, v[0:1], off
	v_add_u32_e32 v0, s1, v10
	v_ashrrev_i32_e32 v1, 31, v0
	v_lshlrev_b64 v[0:1], 12, v[0:1]
	v_lshl_add_u64 v[0:1], s[6:7], 0, v[0:1]
	v_lshl_add_u64 v[0:1], v[0:1], 0, v[2:3]
	global_load_dword v116, v[0:1], off
	v_add_u32_e32 v0, s1, v11
	v_ashrrev_i32_e32 v1, 31, v0
	v_lshlrev_b64 v[0:1], 12, v[0:1]
	v_lshl_add_u64 v[0:1], s[6:7], 0, v[0:1]
	v_lshl_add_u64 v[0:1], v[0:1], 0, v[2:3]
	global_load_dword v117, v[0:1], off
	v_add_u32_e32 v0, s1, v12
	v_ashrrev_i32_e32 v1, 31, v0
	v_lshlrev_b64 v[0:1], 12, v[0:1]
	v_lshl_add_u64 v[0:1], s[6:7], 0, v[0:1]
	v_lshl_add_u64 v[0:1], v[0:1], 0, v[2:3]
	global_load_dword v118, v[0:1], off
	v_add_u32_e32 v0, s1, v13
	v_ashrrev_i32_e32 v1, 31, v0
	v_lshlrev_b64 v[0:1], 12, v[0:1]
	v_lshl_add_u64 v[0:1], s[6:7], 0, v[0:1]
	v_lshl_add_u64 v[0:1], v[0:1], 0, v[2:3]
	global_load_dword v119, v[0:1], off
	v_mul_u32_u24_e32 v2, 0x104, v5
	v_lshlrev_b32_e32 v3, 2, v4
	s_lshl_b32 s1, s1, 1
	s_add_u32 s22, s21, s1
	v_readlane_b32 s1, v250, 49
	s_addc_u32 s23, s1, 0
	s_movk_i32 s1, 0x7fff
	v_add_u32_e32 v4, s0, v4
	s_waitcnt vmcnt(0)
	ds_write_b32 v6, v112
	ds_write_b32 v6, v113 offset:2080
	ds_write_b32 v6, v114 offset:4160
	ds_write_b32 v6, v115 offset:6240
	ds_write_b32 v6, v116 offset:8320
	ds_write_b32 v6, v117 offset:10400
	ds_write_b32 v6, v118 offset:12480
	ds_write_b32 v6, v119 offset:14560
	v_add3_u32 v6, 0, v2, v3
	s_waitcnt lgkmcnt(0)
	s_barrier
	ds_read2_b32 v[2:3], v6 offset1:8
	v_lshl_add_u64 v[0:1], s[22:23], 0, v[16:17]
	s_waitcnt lgkmcnt(0)
	v_bfe_u32 v5, v2, 16, 1
	v_add3_u32 v2, v2, v5, s1
	v_ashrrev_i32_e32 v5, 31, v4
	v_lshlrev_b64 v[4:5], 11, v[4:5]
	v_lshl_add_u64 v[4:5], v[0:1], 0, v[4:5]
	global_store_short_d16_hi v[4:5], v2, off
	v_bfe_u32 v2, v3, 16, 1
	v_add3_u32 v4, v3, v2, s1
	v_add_u32_e32 v2, s0, v7
	v_ashrrev_i32_e32 v3, 31, v2
	v_lshlrev_b64 v[2:3], 11, v[2:3]
	v_lshl_add_u64 v[2:3], v[0:1], 0, v[2:3]
	global_store_short_d16_hi v[2:3], v4, off
	ds_read2_b32 v[2:3], v6 offset0:16 offset1:24
	s_waitcnt lgkmcnt(0)
	v_bfe_u32 v4, v2, 16, 1
	v_add3_u32 v2, v2, v4, s1
	v_add_u32_e32 v4, s0, v8
	v_ashrrev_i32_e32 v5, 31, v4
	v_lshlrev_b64 v[4:5], 11, v[4:5]
	v_lshl_add_u64 v[4:5], v[0:1], 0, v[4:5]
	global_store_short_d16_hi v[4:5], v2, off
	v_bfe_u32 v2, v3, 16, 1
	v_add3_u32 v4, v3, v2, s1
	v_add_u32_e32 v2, s0, v9
	v_ashrrev_i32_e32 v3, 31, v2
	v_lshlrev_b64 v[2:3], 11, v[2:3]
	v_lshl_add_u64 v[2:3], v[0:1], 0, v[2:3]
	global_store_short_d16_hi v[2:3], v4, off
	ds_read2_b32 v[2:3], v6 offset0:32 offset1:40
	s_waitcnt lgkmcnt(0)
	v_bfe_u32 v4, v2, 16, 1
	v_add3_u32 v2, v2, v4, s1
	v_add_u32_e32 v4, s0, v10
	v_ashrrev_i32_e32 v5, 31, v4
	v_lshlrev_b64 v[4:5], 11, v[4:5]
	v_lshl_add_u64 v[4:5], v[0:1], 0, v[4:5]
	global_store_short_d16_hi v[4:5], v2, off
	v_bfe_u32 v2, v3, 16, 1
	v_add3_u32 v4, v3, v2, s1
	v_add_u32_e32 v2, s0, v11
	v_ashrrev_i32_e32 v3, 31, v2
	v_lshlrev_b64 v[2:3], 11, v[2:3]
	v_lshl_add_u64 v[2:3], v[0:1], 0, v[2:3]
	global_store_short_d16_hi v[2:3], v4, off
	ds_read2_b32 v[2:3], v6 offset0:48 offset1:56
	s_waitcnt lgkmcnt(0)
	v_bfe_u32 v4, v2, 16, 1
	v_add3_u32 v2, v2, v4, s1
	v_add_u32_e32 v4, s0, v12
	v_ashrrev_i32_e32 v5, 31, v4
	v_lshlrev_b64 v[4:5], 11, v[4:5]
	v_lshl_add_u64 v[4:5], v[0:1], 0, v[4:5]
	global_store_short_d16_hi v[4:5], v2, off
	v_bfe_u32 v2, v3, 16, 1
	v_add3_u32 v4, v3, v2, s1
	v_add_u32_e32 v2, s0, v13
	v_ashrrev_i32_e32 v3, 31, v2
	v_lshlrev_b64 v[2:3], 11, v[2:3]
	v_lshl_add_u64 v[0:1], v[0:1], 0, v[2:3]
	global_store_short_d16_hi v[0:1], v4, off
	s_barrier

; DI unsigned short f2bf(float x) { unsigned u = __float_as_uint(x); u += 0x7fffu + ((u >> 16) & 1u); return (unsigned short)(u >> 16); }
; DI int otid() { int t = threadIdx.x; asm volatile("" : "+v"(t)); return t; }
;   const int tid = otid();
; #pragma unroll
;   for (int rr = 0; rr < 8; ++rr) {
;     const int kl = rr * 8 + (tid >> 6), nl = tid & 63, np = n0 + nl;
;     int n = np; bool ok = true;
;     if (winmap) { if (np >= 3840) n = np - 56; else if (np >= 3784) ok = false; }
;     tile[kl * 65 + nl] = ok ? src[(size_t)(k0 + kl) * ldsrc + n] : 0.f;
;   }
;   __syncthreads();
; #pragma unroll
;   for (int rr = 0; rr < 8; ++rr) {
;     const int nl = rr * 8 + (tid >> 6), kl = tid & 63;
;     dst[(size_t)(n0 + nl) * K + dk + k0 + kl] = f2bf(tile[kl * 65 + nl]);
;   }
;   __syncthreads();
; }
; DI void convert_layer(const Params& p, int l, char* smem) {
;     ...
;     else if (it < 1600) { int i = it - 1472; int nt = i >> 3, kt = i & 7; tconv_tile(p.w_pa + (size_t)l * 512 * 1024, 1024, 1024, (reinterpret_cast<bf16_t*>(p.ws + OFF_WPAT)), nt * 64, kt * 64, false, tile); }
.LBB0_2784:
	s_andn2_b64 vcc, exec, s[0:1]
	s_cbranch_vccnz .LBB0_2786
	v_mov_b32_e32 v0, v153
	s_and_b32 s1, s15, 0x1c0
	s_and_b32 s0, s16, 0x3fc0
	v_ashrrev_i32_e32 v4, 6, v0
	v_and_b32_e32 v5, 63, v0
	v_add_u32_e32 v0, s1, v4
	s_addk_i32 s0, 0xd200
	v_ashrrev_i32_e32 v1, 31, v0
	v_or_b32_e32 v16, s0, v5
	v_lshlrev_b64 v[0:1], 12, v[0:1]
	v_lshl_add_u64 v[0:1], s[8:9], 0, v[0:1]
	v_lshlrev_b64 v[2:3], 2, v[16:17]
	v_lshl_add_u64 v[0:1], v[0:1], 0, v[2:3]
	global_load_dword v112, v[0:1], off
	s_movk_i32 s21, 0x104
	v_lshlrev_b32_e32 v6, 2, v5
	v_mul_lo_u32 v1, v4, s21
	v_add3_u32 v6, 0, v6, v1
	v_add_u32_e32 v7, 8, v4
	v_add_u32_e32 v8, 16, v4
	v_add_u32_e32 v9, 24, v4
	v_add_u32_e32 v10, 32, v4
	v_add_u32_e32 v11, 40, v4
	v_add_u32_e32 v12, 48, v4
	v_add_u32_e32 v13, 56, v4
	v_readlane_b32 s21, v250, 40
	v_lshlrev_b32_e32 v16, 1, v5
	v_add_u32_e32 v0, s1, v7
	v_ashrrev_i32_e32 v1, 31, v0
	v_lshlrev_b64 v[0:1], 12, v[0:1]
	v_lshl_add_u64 v[0:1], s[8:9], 0, v[0:1]
	v_lshl_add_u64 v[0:1], v[0:1], 0, v[2:3]
	global_load_dword v113, v[0:1], off
	v_add_u32_e32 v0, s1, v8
	v_ashrrev_i32_e32 v1, 31, v0
	v_lshlrev_b64 v[0:1], 12, v[0:1]
	v_lshl_add_u64 v[0:1], s[8:9], 0, v[0:1]
	v_lshl_add_u64 v[0:1], v[0:1], 0, v[2:3]
	global_load_dword v114, v[0:1], off
	v_add_u32_e32 v0, s1, v9
	v_ashrrev_i32_e32 v1, 31, v0
	v_lshlrev_b64 v[0:1], 12, v[0:1]
	v_lshl_add_u64 v[0:1], s[8:9], 0, v[0:1]
	v_lshl_add_u64 v[0:1], v[0:1], 0, v[2:3]
	global_load_dword v115, v[0:1], off
	v_add_u32_e32 v0, s1, v10
	v_ashrrev_i32_e32 v1, 31, v0
	v_lshlrev_b64 v[0:1], 12, v[0:1]
	v_lshl_add_u64 v[0:1], s[8:9], 0, v[0:1]
	v_lshl_add_u64 v[0:1], v[0:1], 0, v[2:3]
	global_load_dword v116, v[0:1], off
	v_add_u32_e32 v0, s1, v11
	v_ashrrev_i32_e32 v1, 31, v0
	v_lshlrev_b64 v[0:1], 12, v[0:1]
	v_lshl_add_u64 v[0:1], s[8:9], 0, v[0:1]
	v_lshl_add_u64 v[0:1], v[0:1], 0, v[2:3]
	global_load_dword v117, v[0:1], off
	v_add_u32_e32 v0, s1, v12
	v_ashrrev_i32_e32 v1, 31, v0
	v_lshlrev_b64 v[0:1], 12, v[0:1]
	v_lshl_add_u64 v[0:1], s[8:9], 0, v[0:1]
	v_lshl_add_u64 v[0:1], v[0:1], 0, v[2:3]
	global_load_dword v118, v[0:1], off
	v_add_u32_e32 v0, s1, v13
	v_ashrrev_i32_e32 v1, 31, v0
	v_lshlrev_b64 v[0:1], 12, v[0:1]
	v_lshl_add_u64 v[0:1], s[8:9], 0, v[0:1]
	v_lshl_add_u64 v[0:1], v[0:1], 0, v[2:3]
	global_load_dword v119, v[0:1], off
	v_mul_u32_u24_e32 v2, 0x104, v5
	v_lshlrev_b32_e32 v3, 2, v4
	s_lshl_b32 s1, s1, 1
	s_add_u32 s22, s21, s1
	v_readlane_b32 s1, v250, 41
	s_addc_u32 s23, s1, 0
	s_movk_i32 s1, 0x7fff
	v_add_u32_e32 v4, s0, v4
	s_waitcnt vmcnt(0)
	ds_write_b32 v6, v112
	ds_write_b32 v6, v113 offset:2080
	ds_write_b32 v6, v114 offset:4160
	ds_write_b32 v6, v115 offset:6240
	ds_write_b32 v6, v116 offset:8320
	ds_write_b32 v6, v117 offset:10400
	ds_write_b32 v6, v118 offset:12480
	ds_write_b32 v6, v119 offset:14560
	v_add3_u32 v6, 0, v2, v3
	s_waitcnt lgkmcnt(0)
	s_barrier
	ds_read2_b32 v[2:3], v6 offset1:8
	v_lshl_add_u64 v[0:1], s[22:23], 0, v[16:17]
	s_waitcnt lgkmcnt(0)
	v_bfe_u32 v5, v2, 16, 1
	v_add3_u32 v2, v2, v5, s1
	v_ashrrev_i32_e32 v5, 31, v4
	v_lshlrev_b64 v[4:5], 11, v[4:5]
	v_lshl_add_u64 v[4:5], v[0:1], 0, v[4:5]
	global_store_short_d16_hi v[4:5], v2, off
	v_bfe_u32 v2, v3, 16, 1
	v_add3_u32 v4, v3, v2, s1
	v_add_u32_e32 v2, s0, v7
	v_ashrrev_i32_e32 v3, 31, v2
	v_lshlrev_b64 v[2:3], 11, v[2:3]
	v_lshl_add_u64 v[2:3], v[0:1], 0, v[2:3]
	global_store_short_d16_hi v[2:3], v4, off
	ds_read2_b32 v[2:3], v6 offset0:16 offset1:24
	s_waitcnt lgkmcnt(0)
	v_bfe_u32 v4, v2, 16, 1
	v_add3_u32 v2, v2, v4, s1
	v_add_u32_e32 v4, s0, v8
	v_ashrrev_i32_e32 v5, 31, v4
	v_lshlrev_b64 v[4:5], 11, v[4:5]
	v_lshl_add_u64 v[4:5], v[0:1], 0, v[4:5]
	global_store_short_d16_hi v[4:5], v2, off
	v_bfe_u32 v2, v3, 16, 1
	v_add3_u32 v4, v3, v2, s1
	v_add_u32_e32 v2, s0, v9
	v_ashrrev_i32_e32 v3, 31, v2
	v_lshlrev_b64 v[2:3], 11, v[2:3]
	v_lshl_add_u64 v[2:3], v[0:1], 0, v[2:3]
	global_store_short_d16_hi v[2:3], v4, off
	ds_read2_b32 v[2:3], v6 offset0:32 offset1:40
	s_waitcnt lgkmcnt(0)
	v_bfe_u32 v4, v2, 16, 1
	v_add3_u32 v2, v2, v4, s1
	v_add_u32_e32 v4, s0, v10
	v_ashrrev_i32_e32 v5, 31, v4
	v_lshlrev_b64 v[4:5], 11, v[4:5]
	v_lshl_add_u64 v[4:5], v[0:1], 0, v[4:5]
	global_store_short_d16_hi v[4:5], v2, off
	v_bfe_u32 v2, v3, 16, 1
	v_add3_u32 v4, v3, v2, s1
	v_add_u32_e32 v2, s0, v11
	v_ashrrev_i32_e32 v3, 31, v2
	v_lshlrev_b64 v[2:3], 11, v[2:3]
	v_lshl_add_u64 v[2:3], v[0:1], 0, v[2:3]
	global_store_short_d16_hi v[2:3], v4, off
	ds_read2_b32 v[2:3], v6 offset0:48 offset1:56
	s_waitcnt lgkmcnt(0)
	v_bfe_u32 v4, v2, 16, 1
	v_add3_u32 v2, v2, v4, s1
	v_add_u32_e32 v4, s0, v12
	v_ashrrev_i32_e32 v5, 31, v4
	v_lshlrev_b64 v[4:5], 11, v[4:5]
	v_lshl_add_u64 v[4:5], v[0:1], 0, v[4:5]
	global_store_short_d16_hi v[4:5], v2, off
	v_bfe_u32 v2, v3, 16, 1
	v_add3_u32 v4, v3, v2, s1
	v_add_u32_e32 v2, s0, v13
	v_ashrrev_i32_e32 v3, 31, v2
	v_lshlrev_b64 v[2:3], 11, v[2:3]
	v_lshl_add_u64 v[0:1], v[0:1], 0, v[2:3]
	global_store_short_d16_hi v[0:1], v4, off
	s_barrier

; DI unsigned short f2bf(float x) { unsigned u = __float_as_uint(x); u += 0x7fffu + ((u >> 16) & 1u); return (unsigned short)(u >> 16); }
; DI int otid() { int t = threadIdx.x; asm volatile("" : "+v"(t)); return t; }
;   const int tid = otid();
; #pragma unroll
;   for (int rr = 0; rr < 8; ++rr) {
;     const int kl = rr * 8 + (tid >> 6), nl = tid & 63, np = n0 + nl;
;     int n = np; bool ok = true;
;     if (winmap) { if (np >= 3840) n = np - 56; else if (np >= 3784) ok = false; }
;     tile[kl * 65 + nl] = ok ? src[(size_t)(k0 + kl) * ldsrc + n] : 0.f;
;   }
; DI void convert_layer(const Params& p, int l, char* smem) {
;     ...
;   for (int idx = gtid; idx < 8 * 1024 * 512; idx += gn) {
;     int b = idx >> 19, rem = idx & ((1 << 19) - 1);
;     (reinterpret_cast<bf16_t*>(p.ws + OFF_KAS))[(size_t)b * LS * 512 + rem] = f2bf(p.c_sb_k[(size_t)l * 8 * 1024 * 512 + idx]);
;   }
; #pragma unroll 4
;   for (int idx = gtid; idx < 8 * 512 * 1024; idx += gn) {
;     int b = idx >> 19, hd = (idx >> 10) & 511, t = idx & 1023;
;     (reinterpret_cast<bf16_t*>(p.ws + OFF_VATS))[((size_t)b * 512 + hd) * LS + t] = f2bf(p.c_sb_v[(((size_t)l * 8 + b) * 1024 + t) * 512 + hd]);
;   }
;   for (int idx = gtid; idx < 8 * 1024 * 64; idx += gn) {
;     int b = idx >> 16, rem = idx & 65535;
;     (reinterpret_cast<bf16_t*>(p.ws + OFF_KBS))[(size_t)b * LS * 64 + rem] = f2bf(p.c_dsa_k[(size_t)l * 8 * 65536 + idx]);
;     (reinterpret_cast<bf16_t*>(p.ws + OFF_KIS))[(size_t)b * LS * 64 + rem] = f2bf(p.c_idx_k[(size_t)l * 8 * 65536 + idx]);
;     int d = (idx >> 10) & 63, t = idx & 1023;
;     (reinterpret_cast<bf16_t*>(p.ws + OFF_VBTS))[((size_t)b * 64 + d) * LS + t] = f2bf(p.c_dsa_v[(((size_t)l * 8 + b) * 1024 + t) * 64 + d]);
;   }
.LBB0_2787:
	s_andn2_b64 vcc, exec, s[0:1]
	s_cbranch_vccnz .LBB0_2776
	v_mov_b32_e32 v3, v153
	s_movk_i32 s0, 0xeff
	v_bfi_b32 v0, 63, v3, s17
	v_subrev_u32_e32 v1, 56, v0
	v_add_u32_e32 v4, 0xfffff138, v0
	v_cmp_lt_i32_e64 s[0:1], s0, v0
	s_and_b32 s21, s15, 0x3c0
	v_ashrrev_i32_e32 v2, 6, v3
	v_cmp_lt_u32_e32 vcc, 55, v4
	v_mov_b32_e32 v5, 0
	v_cndmask_b32_e64 v0, v0, v1, s[0:1]
	v_mov_b32_e32 v1, 0
	v_mov_b32_e32 v112, 0
	v_mov_b32_e32 v113, 0
	v_mov_b32_e32 v114, 0
	v_mov_b32_e32 v115, 0
	v_mov_b32_e32 v116, 0
	v_mov_b32_e32 v117, 0
	v_mov_b32_e32 v118, 0
	v_mov_b32_e32 v119, 0
	s_and_saveexec_b64 s[0:1], vcc
	s_cbranch_execz .Ltw1_skip
	v_add_u32_e32 v4, s21, v2
	v_mov_b64_e32 v[6:7], s[10:11]
	s_movk_i32 s22, 0x5b20
	v_ashrrev_i32_e32 v1, 31, v0
	v_mad_i64_i32 v[6:7], s[22:23], v4, s22, v[6:7]
	v_lshl_add_u64 v[6:7], v[0:1], 2, v[6:7]
	s_mov_b64 s[24:25], 0x2d900
	global_load_dword v112, v[6:7], off
	v_lshl_add_u64 v[6:7], v[6:7], 0, s[24:25]
	global_load_dword v113, v[6:7], off
	v_lshl_add_u64 v[6:7], v[6:7], 0, s[24:25]
	global_load_dword v114, v[6:7], off
	v_lshl_add_u64 v[6:7], v[6:7], 0, s[24:25]
	global_load_dword v115, v[6:7], off
	v_lshl_add_u64 v[6:7], v[6:7], 0, s[24:25]
	global_load_dword v116, v[6:7], off
	v_lshl_add_u64 v[6:7], v[6:7], 0, s[24:25]
	global_load_dword v117, v[6:7], off
	v_lshl_add_u64 v[6:7], v[6:7], 0, s[24:25]
	global_load_dword v118, v[6:7], off
	v_lshl_add_u64 v[6:7], v[6:7], 0, s[24:25]
	global_load_dword v119, v[6:7], off
.Ltw1_skip:
	s_or_b64 exec, exec, s[0:1]
	v_and_b32_e32 v4, 63, v153
	s_movk_i32 s22, 0x104
	v_lshl_add_u32 v6, v4, 2, 0
	v_mul_lo_u32 v3, v2, s22
	v_add_u32_e32 v9, v6, v3
	v_add_u32_e32 v3, 8, v2
	v_add_u32_e32 v5, 16, v2
	v_add_u32_e32 v7, 24, v2
	v_add_u32_e32 v8, 32, v2
	v_add_u32_e32 v10, 40, v2
	v_add_u32_e32 v11, 48, v2
	v_add_u32_e32 v12, 56, v2
	s_waitcnt vmcnt(0)
	ds_write_b32 v9, v112
	ds_write_b32 v9, v113 offset:2080
	ds_write_b32 v9, v114 offset:4160
	ds_write_b32 v9, v115 offset:6240
	ds_write_b32 v9, v116 offset:8320
	ds_write_b32 v9, v117 offset:10400
	ds_write_b32 v9, v118 offset:12480
	v_mov_b32_e32 v13, v119
	s_branch .LBB0_2775
.LBB0_2804:
	v_readlane_b32 s20, v249, 6
	s_nop 3
	s_cmpk_eq_i32 s20, 0x100
	s_cbranch_scc0 .Lcc1_old
	v_readlane_b32 s20, v249, 8
	v_readlane_b32 s24, v249, 0
	v_readlane_b32 s25, v249, 1
	v_readlane_b32 s26, v249, 14
	v_readlane_b32 s27, v249, 15
	v_readlane_b32 s28, v249, 16
	v_readlane_b32 s29, v249, 17
	v_readlane_b32 s30, v249, 18
	v_readlane_b32 s31, v249, 19
	v_readlane_b32 s32, v249, 20
	v_readlane_b32 s33, v249, 21
	v_readlane_b32 s34, v249, 22
	v_readlane_b32 s35, v249, 23
	v_readlane_b32 s22, v251, 6
	s_nop 3
	v_add_u32_e32 v18, s20, v153
	v_mov_b32_e32 v16, 0
	s_lshl_b32 s36, s22, 24
	s_lshl_b32 s37, s22, 21
	s_add_u32 s26, s26, s36
	s_addc_u32 s27, s27, 0
	s_add_u32 s28, s28, s36
	s_addc_u32 s29, s29, 0
	s_add_u32 s30, s30, s37
	s_addc_u32 s31, s31, 0
	s_add_u32 s32, s32, s37
	s_addc_u32 s33, s33, 0
	s_add_u32 s34, s34, s37
	s_addc_u32 s35, s35, 0
	v_lshlrev_b32_e32 v1, 4, v18
	v_lshlrev_b32_e32 v2, 3, v18
	v_and_b32_e32 v9, 0x3ff, v18
	v_lshrrev_b32_e32 v10, 10, v18
	v_lshlrev_b32_e32 v4, 11, v9
	v_lshl_add_u32 v4, v10, 4, v4
	v_lshlrev_b32_e32 v5, 1, v9
	v_mov_b32_e32 v11, 0x2200
	v_mad_u32_u24 v5, v10, v11, v5
	v_lshrrev_b32_e32 v12, 14, v18
	v_and_b32_e32 v13, 0x3fff, v18
	v_lshlrev_b32_e32 v6, 3, v13
	v_mov_b32_e32 v14, 0x22000
	v_mad_u32_u24 v6, v12, v14, v6
	v_bfe_u32 v15, v18, 10, 4
	v_lshlrev_b32_e32 v7, 18, v12
	v_lshl_add_u32 v7, v9, 8, v7
	v_lshl_add_u32 v7, v15, 4, v7
	v_lshlrev_b32_e32 v8, 1, v9
	v_mad_u32_u24 v8, v15, v11, v8
	v_mad_u32_u24 v8, v12, v14, v8
	s_add_u32 s38, s26, 0x0
	s_addc_u32 s39, s27, 0
	global_load_dwordx4 v[112:115], v1, s[38:39]
	s_add_u32 s40, s26, 0x200000
	s_addc_u32 s41, s27, 0
	global_load_dwordx4 v[116:119], v1, s[40:41]
	s_add_u32 s38, s26, 0x400000
	s_addc_u32 s39, s27, 0
	global_load_dwordx4 v[120:123], v1, s[38:39]
	s_add_u32 s40, s26, 0x600000
	s_addc_u32 s41, s27, 0
	global_load_dwordx4 v[124:127], v1, s[40:41]
	s_add_u32 s38, s26, 0x800000
	s_addc_u32 s39, s27, 0
	global_load_dwordx4 v[128:131], v1, s[38:39]
	s_add_u32 s40, s26, 0xa00000
	s_addc_u32 s41, s27, 0
	global_load_dwordx4 v[132:135], v1, s[40:41]
	s_add_u32 s38, s26, 0xc00000
	s_addc_u32 s39, s27, 0
	global_load_dwordx4 v[136:139], v1, s[38:39]
	s_add_u32 s40, s26, 0xe00000
	s_addc_u32 s41, s27, 0
	global_load_dwordx4 v[140:143], v1, s[40:41]
	s_add_u32 s38, s28, 0x0
	s_addc_u32 s39, s29, 0
	global_load_dwordx4 v[24:27], v4, s[38:39]
	s_add_u32 s40, s28, 0x200000
	s_addc_u32 s41, s29, 0
	global_load_dwordx4 v[28:31], v4, s[40:41]
	s_add_u32 s38, s28, 0x400000
	s_addc_u32 s39, s29, 0
	global_load_dwordx4 v[32:35], v4, s[38:39]
	s_add_u32 s40, s28, 0x600000
	s_addc_u32 s41, s29, 0
	global_load_dwordx4 v[36:39], v4, s[40:41]
	s_add_u32 s38, s28, 0x800000
	s_addc_u32 s39, s29, 0
	global_load_dwordx4 v[40:43], v4, s[38:39]
	s_add_u32 s40, s28, 0xa00000
	s_addc_u32 s41, s29, 0
	global_load_dwordx4 v[44:47], v4, s[40:41]
	s_add_u32 s38, s28, 0xc00000
	s_addc_u32 s39, s29, 0
	global_load_dwordx4 v[48:51], v4, s[38:39]
	s_add_u32 s40, s28, 0xe00000
	s_addc_u32 s41, s29, 0
	global_load_dwordx4 v[52:55], v4, s[40:41]
	global_load_dwordx4 v[144:147], v1, s[30:31]
	global_load_dwordx4 v[148:151], v1, s[34:35]
	global_load_dwordx4 v[56:59], v7, s[32:33]
	s_add_u32 s42, s24, 0x24380000
	s_addc_u32 s43, s25, 0
	s_waitcnt vmcnt(18)
	v_cvt_pk_bf16_f32 v112, v112, v113
	v_cvt_pk_bf16_f32 v113, v114, v115
	global_store_dwordx2 v2, v[112:113], s[42:43]
	s_add_u32 s44, s24, 0x24490000
	s_addc_u32 s45, s25, 0
	s_waitcnt vmcnt(18)
; DI unsigned short f2bf(float x) { unsigned u = __float_as_uint(x); u += 0x7fffu + ((u >> 16) & 1u); return (unsigned short)(u >> 16); }
; DI void convert_layer(const Params& p, int l, char* smem) {
;     ...
;   for (int idx = gtid; idx < 8 * 1024 * 512; idx += gn) {
;     int b = idx >> 19, rem = idx & ((1 << 19) - 1);
;     (reinterpret_cast<bf16_t*>(p.ws + OFF_KAS))[(size_t)b * LS * 512 + rem] = f2bf(p.c_sb_k[(size_t)l * 8 * 1024 * 512 + idx]);
;   }
; #pragma unroll 4
;   for (int idx = gtid; idx < 8 * 512 * 1024; idx += gn) {
;     int b = idx >> 19, hd = (idx >> 10) & 511, t = idx & 1023;
;     (reinterpret_cast<bf16_t*>(p.ws + OFF_VATS))[((size_t)b * 512 + hd) * LS + t] = f2bf(p.c_sb_v[(((size_t)l * 8 + b) * 1024 + t) * 512 + hd]);
;   }
;   for (int idx = gtid; idx < 8 * 1024 * 64; idx += gn) {
;     int b = idx >> 16, rem = idx & 65535;
;     (reinterpret_cast<bf16_t*>(p.ws + OFF_KBS))[(size_t)b * LS * 64 + rem] = f2bf(p.c_dsa_k[(size_t)l * 8 * 65536 + idx]);
;     (reinterpret_cast<bf16_t*>(p.ws + OFF_KIS))[(size_t)b * LS * 64 + rem] = f2bf(p.c_idx_k[(size_t)l * 8 * 65536 + idx]);
;     int d = (idx >> 10) & 63, t = idx & 1023;
;     (reinterpret_cast<bf16_t*>(p.ws + OFF_VBTS))[((size_t)b * 64 + d) * LS + t] = f2bf(p.c_dsa_v[(((size_t)l * 8 + b) * 1024 + t) * 64 + d]);
;   }
	v_cvt_pk_bf16_f32 v116, v116, v117
	v_cvt_pk_bf16_f32 v117, v118, v119
	global_store_dwordx2 v2, v[116:117], s[44:45]
	s_add_u32 s42, s24, 0x245a0000
	s_addc_u32 s43, s25, 0
	s_waitcnt vmcnt(18)
	v_cvt_pk_bf16_f32 v120, v120, v121
	v_cvt_pk_bf16_f32 v121, v122, v123
	global_store_dwordx2 v2, v[120:121], s[42:43]
	s_add_u32 s44, s24, 0x246b0000
	s_addc_u32 s45, s25, 0
	s_waitcnt vmcnt(18)
	v_cvt_pk_bf16_f32 v124, v124, v125
	v_cvt_pk_bf16_f32 v125, v126, v127
	global_store_dwordx2 v2, v[124:125], s[44:45]
	s_add_u32 s42, s24, 0x247c0000
	s_addc_u32 s43, s25, 0
	s_waitcnt vmcnt(18)
	v_cvt_pk_bf16_f32 v128, v128, v129
	v_cvt_pk_bf16_f32 v129, v130, v131
	global_store_dwordx2 v2, v[128:129], s[42:43]
	s_add_u32 s44, s24, 0x248d0000
	s_addc_u32 s45, s25, 0
	s_waitcnt vmcnt(18)
	v_cvt_pk_bf16_f32 v132, v132, v133
	v_cvt_pk_bf16_f32 v133, v134, v135
	global_store_dwordx2 v2, v[132:133], s[44:45]
	s_add_u32 s42, s24, 0x249e0000
	s_addc_u32 s43, s25, 0
	s_waitcnt vmcnt(18)
	v_cvt_pk_bf16_f32 v136, v136, v137
	v_cvt_pk_bf16_f32 v137, v138, v139
	global_store_dwordx2 v2, v[136:137], s[42:43]
	s_add_u32 s44, s24, 0x24af0000
	s_addc_u32 s45, s25, 0
	s_waitcnt vmcnt(18)
	v_cvt_pk_bf16_f32 v140, v140, v141
	v_cvt_pk_bf16_f32 v141, v142, v143
	global_store_dwordx2 v2, v[140:141], s[44:45]
	s_waitcnt vmcnt(18)
	s_add_u32 s42, s24, 0x24c00000
	s_addc_u32 s43, s25, 0
	v_cvt_pk_bf16_f32 v24, v16, v24
	global_store_short_d16_hi v5, v24, s[42:43]
	v_cvt_pk_bf16_f32 v25, v16, v25
	global_store_short_d16_hi v5, v25, s[42:43] offset:2176
	s_add_u32 s44, s24, 0x24c01100
	s_addc_u32 s45, s25, 0
	v_cvt_pk_bf16_f32 v26, v16, v26
	global_store_short_d16_hi v5, v26, s[44:45]
	v_cvt_pk_bf16_f32 v27, v16, v27
	global_store_short_d16_hi v5, v27, s[44:45] offset:2176
	s_waitcnt vmcnt(21)
	s_add_u32 s42, s24, 0x24d10000
	s_addc_u32 s43, s25, 0
	v_cvt_pk_bf16_f32 v28, v16, v28
	global_store_short_d16_hi v5, v28, s[42:43]
	v_cvt_pk_bf16_f32 v29, v16, v29
	global_store_short_d16_hi v5, v29, s[42:43] offset:2176
	s_add_u32 s44, s24, 0x24d11100
	s_addc_u32 s45, s25, 0
	v_cvt_pk_bf16_f32 v30, v16, v30
	global_store_short_d16_hi v5, v30, s[44:45]
	v_cvt_pk_bf16_f32 v31, v16, v31
	global_store_short_d16_hi v5, v31, s[44:45] offset:2176
	s_waitcnt vmcnt(24)
	s_add_u32 s42, s24, 0x24e20000
	s_addc_u32 s43, s25, 0
	v_cvt_pk_bf16_f32 v32, v16, v32
	global_store_short_d16_hi v5, v32, s[42:43]
	v_cvt_pk_bf16_f32 v33, v16, v33
	global_store_short_d16_hi v5, v33, s[42:43] offset:2176
	s_add_u32 s44, s24, 0x24e21100
	s_addc_u32 s45, s25, 0
	v_cvt_pk_bf16_f32 v34, v16, v34
	global_store_short_d16_hi v5, v34, s[44:45]
	v_cvt_pk_bf16_f32 v35, v16, v35
	global_store_short_d16_hi v5, v35, s[44:45] offset:2176
	s_waitcnt vmcnt(27)
	s_add_u32 s42, s24, 0x24f30000
	s_addc_u32 s43, s25, 0
	v_cvt_pk_bf16_f32 v36, v16, v36
	global_store_short_d16_hi v5, v36, s[42:43]
	v_cvt_pk_bf16_f32 v37, v16, v37
	global_store_short_d16_hi v5, v37, s[42:43] offset:2176
	s_add_u32 s44, s24, 0x24f31100
	s_addc_u32 s45, s25, 0
	v_cvt_pk_bf16_f32 v38, v16, v38
	global_store_short_d16_hi v5, v38, s[44:45]
	v_cvt_pk_bf16_f32 v39, v16, v39
	global_store_short_d16_hi v5, v39, s[44:45] offset:2176
	s_waitcnt vmcnt(30)
	s_add_u32 s42, s24, 0x25040000
	s_addc_u32 s43, s25, 0
	v_cvt_pk_bf16_f32 v40, v16, v40
	global_store_short_d16_hi v5, v40, s[42:43]
	v_cvt_pk_bf16_f32 v41, v16, v41
	global_store_short_d16_hi v5, v41, s[42:43] offset:2176
	s_add_u32 s44, s24, 0x25041100
	s_addc_u32 s45, s25, 0
	v_cvt_pk_bf16_f32 v42, v16, v42
	global_store_short_d16_hi v5, v42, s[44:45]
	v_cvt_pk_bf16_f32 v43, v16, v43
	global_store_short_d16_hi v5, v43, s[44:45] offset:2176
	s_waitcnt vmcnt(33)
	s_add_u32 s42, s24, 0x25150000
	s_addc_u32 s43, s25, 0
	v_cvt_pk_bf16_f32 v44, v16, v44
	global_store_short_d16_hi v5, v44, s[42:43]
	v_cvt_pk_bf16_f32 v45, v16, v45
	global_store_short_d16_hi v5, v45, s[42:43] offset:2176
	s_add_u32 s44, s24, 0x25151100
	s_addc_u32 s45, s25, 0
	v_cvt_pk_bf16_f32 v46, v16, v46
	global_store_short_d16_hi v5, v46, s[44:45]
	v_cvt_pk_bf16_f32 v47, v16, v47
	global_store_short_d16_hi v5, v47, s[44:45] offset:2176
	s_waitcnt vmcnt(36)
	s_add_u32 s42, s24, 0x25260000
	s_addc_u32 s43, s25, 0
	v_cvt_pk_bf16_f32 v48, v16, v48
	global_store_short_d16_hi v5, v48, s[42:43]
	v_cvt_pk_bf16_f32 v49, v16, v49
	global_store_short_d16_hi v5, v49, s[42:43] offset:2176
	s_add_u32 s44, s24, 0x25261100
	s_addc_u32 s45, s25, 0
	v_cvt_pk_bf16_f32 v50, v16, v50
	global_store_short_d16_hi v5, v50, s[44:45]
	v_cvt_pk_bf16_f32 v51, v16, v51
	global_store_short_d16_hi v5, v51, s[44:45] offset:2176
	s_waitcnt vmcnt(39)
	s_add_u32 s42, s24, 0x25370000
	s_addc_u32 s43, s25, 0
	v_cvt_pk_bf16_f32 v52, v16, v52
	global_store_short_d16_hi v5, v52, s[42:43]
	v_cvt_pk_bf16_f32 v53, v16, v53
	global_store_short_d16_hi v5, v53, s[42:43] offset:2176
	s_add_u32 s44, s24, 0x25371100
	s_addc_u32 s45, s25, 0
	v_cvt_pk_bf16_f32 v54, v16, v54
	global_store_short_d16_hi v5, v54, s[44:45]
	v_cvt_pk_bf16_f32 v55, v16, v55
	global_store_short_d16_hi v5, v55, s[44:45] offset:2176
	s_add_u32 s42, s24, 0x26c80000
	s_addc_u32 s43, s25, 0
	s_waitcnt vmcnt(42)
	v_cvt_pk_bf16_f32 v144, v144, v145
	v_cvt_pk_bf16_f32 v145, v146, v147
	global_store_dwordx2 v6, v[144:145], s[42:43]
	s_add_u32 s44, s24, 0x26ea0000
	s_addc_u32 s45, s25, 0
	s_waitcnt vmcnt(42)
	v_cvt_pk_bf16_f32 v148, v148, v149
	v_cvt_pk_bf16_f32 v149, v150, v151
	global_store_dwordx2 v6, v[148:149], s[44:45]
	s_waitcnt vmcnt(42)
	s_add_u32 s42, s24, 0x26d90000
	s_addc_u32 s43, s25, 0
	v_cvt_pk_bf16_f32 v56, v16, v56
	global_store_short_d16_hi v8, v56, s[42:43]
	v_cvt_pk_bf16_f32 v57, v16, v57
	global_store_short_d16_hi v8, v57, s[42:43] offset:2176
	s_add_u32 s44, s24, 0x26d91100
	s_addc_u32 s45, s25, 0
	v_cvt_pk_bf16_f32 v58, v16, v58
	global_store_short_d16_hi v8, v58, s[44:45]
	v_cvt_pk_bf16_f32 v59, v16, v59
	global_store_short_d16_hi v8, v59, s[44:45] offset:2176
	s_branch .LBB0_2847
